# MLA items remapped so the 8 q-block pairs of one (batch,head) run on one XCD (shared K/V in that L2)
# speedup vs baseline: 1.0098x; 1.0056x over previous
.LBB0_1419:
	s_and_b32 s8, s82, 7
	s_lshr_b32 s9, s82, 3
	s_and_b32 s10, s9, 0x18
	s_add_i32 s8, s8, s10
	s_and_b32 s9, s9, 7
	s_lshl_b32 s8, s8, 3
	s_or_b32 s84, s8, s9
	s_ashr_i32 s8, s84, 3
	s_ashr_i32 s10, s84, 6
	s_lshl_b32 s9, s84, 8
	s_and_b32 s12, s8, 7
	s_ashr_i32 s11, s10, 31
	s_and_b32 s83, s9, 0x700
	s_lshl_b64 s[30:31], s[10:11], 12
	s_xor_b32 s84, s83, 0xf00
	s_mul_i32 s9, s12, 0xc0
	s_add_u32 s85, s1, s9
	s_addc_u32 s86, s17, 0
	s_ashr_i32 s9, s8, 31
	s_mul_i32 s11, s8, 0xc0000
	s_mul_hi_i32 s10, s8, 0xc0000
	s_add_u32 s50, s40, s11
	s_addc_u32 s51, s42, s10
	s_lshl_b64 s[52:53], s[8:9], 19
	s_add_u32 s54, s43, s52
	s_addc_u32 s55, s44, s53
	s_lshl_b32 s8, s12, 7
	s_add_u32 s87, s48, s8
	s_addc_u32 s88, s66, 0
	s_add_u32 s58, s50, 0xb000
	s_addc_u32 s59, s51, 0
	s_mov_b64 s[70:71], -1
	s_branch .LBB0_1421
